# A/B: per-phase s_setprio flips deleted from the in-projection GEMM main loop (timing-only edit)
# speedup vs baseline: 1.0038x; 1.0038x over previous
.Lgr_g1_1:
	s_waitcnt vmcnt(24)
	s_waitcnt lgkmcnt(0)
	s_barrier
	s_waitcnt lgkmcnt(0)
	v_mfma_f32_16x16x32_bf16 v[126:129], v[166:169], v[204:207], v[126:129]
	v_mfma_f32_16x16x32_bf16 v[122:125], v[174:177], v[204:207], v[122:125]
	v_mfma_f32_16x16x32_bf16 v[110:113], v[166:169], v[212:215], v[110:113]
	v_mfma_f32_16x16x32_bf16 v[106:109], v[174:177], v[212:215], v[106:109]
	v_mfma_f32_16x16x32_bf16 v[94:97], v[166:169], v[220:223], v[94:97]
	v_mfma_f32_16x16x32_bf16 v[90:93], v[174:177], v[220:223], v[90:93]
	v_mfma_f32_16x16x32_bf16 v[78:81], v[166:169], v[228:231], v[78:81]
	v_mfma_f32_16x16x32_bf16 v[74:77], v[174:177], v[228:231], v[74:77]
	v_mfma_f32_16x16x32_bf16 v[126:129], v[170:173], v[208:211], v[126:129]
	v_mfma_f32_16x16x32_bf16 v[122:125], v[178:181], v[208:211], v[122:125]
	v_mfma_f32_16x16x32_bf16 v[110:113], v[170:173], v[216:219], v[110:113]
	v_mfma_f32_16x16x32_bf16 v[106:109], v[178:181], v[216:219], v[106:109]
	v_mfma_f32_16x16x32_bf16 v[94:97], v[170:173], v[224:227], v[94:97]
	v_mfma_f32_16x16x32_bf16 v[90:93], v[178:181], v[224:227], v[90:93]
	v_mfma_f32_16x16x32_bf16 v[78:81], v[170:173], v[232:235], v[78:81]
	v_mfma_f32_16x16x32_bf16 v[74:77], v[178:181], v[232:235], v[74:77]
	v_mfma_f32_16x16x32_bf16 v[118:121], v[182:185], v[204:207], v[118:121]
	v_mfma_f32_16x16x32_bf16 v[114:117], v[190:193], v[204:207], v[114:117]
	v_mfma_f32_16x16x32_bf16 v[102:105], v[182:185], v[212:215], v[102:105]
	v_mfma_f32_16x16x32_bf16 v[98:101], v[190:193], v[212:215], v[98:101]
	v_mfma_f32_16x16x32_bf16 v[86:89], v[182:185], v[220:223], v[86:89]
	v_mfma_f32_16x16x32_bf16 v[82:85], v[190:193], v[220:223], v[82:85]
	v_mfma_f32_16x16x32_bf16 v[70:73], v[182:185], v[228:231], v[70:73]
	v_mfma_f32_16x16x32_bf16 v[66:69], v[190:193], v[228:231], v[66:69]
	v_mfma_f32_16x16x32_bf16 v[118:121], v[186:189], v[208:211], v[118:121]
	v_mfma_f32_16x16x32_bf16 v[114:117], v[200:203], v[208:211], v[114:117]
	v_mfma_f32_16x16x32_bf16 v[102:105], v[186:189], v[216:219], v[102:105]
	v_mfma_f32_16x16x32_bf16 v[98:101], v[200:203], v[216:219], v[98:101]
	v_mfma_f32_16x16x32_bf16 v[86:89], v[186:189], v[224:227], v[86:89]
	v_mfma_f32_16x16x32_bf16 v[82:85], v[200:203], v[224:227], v[82:85]
	v_mfma_f32_16x16x32_bf16 v[70:73], v[186:189], v[232:235], v[70:73]
	v_mfma_f32_16x16x32_bf16 v[66:69], v[200:203], v[232:235], v[66:69]
	s_barrier
	s_add_i32 s5, s5, s22
	v_lshl_add_u64 v[252:253], v[236:237], 0, v[138:139]
	s_mov_b32 m0, s5
	ds_read_b128 v[204:207], v165 offset:16384
	ds_read_b128 v[208:211], v165 offset:17408
	ds_read_b128 v[212:215], v165 offset:18432
	ds_read_b128 v[216:219], v165 offset:19456
	ds_read_b128 v[220:223], v165 offset:20480
	ds_read_b128 v[224:227], v165 offset:21504
	ds_read_b128 v[228:231], v165 offset:22528
	ds_read_b128 v[232:235], v165 offset:23552
	global_load_lds_dwordx4 v[252:253], off
	v_lshl_add_u64 v[242:243], v[236:237], 0, v[134:135]
	s_add_i32 m0, s5, 0x2000
	v_lshl_add_u64 v[244:245], v[236:237], 0, s[64:65]
	s_add_i32 s5, s8, s22
	global_load_lds_dwordx4 v[242:243], off
	v_lshl_add_u64 v[238:239], v[244:245], 0, v[138:139]
	s_mov_b32 m0, s5
	s_nop 0
	global_load_lds_dwordx4 v[238:239], off
	v_lshl_add_u64 v[238:239], v[244:245], 0, v[134:135]
	s_add_i32 m0, s5, 0x2000
	v_lshl_add_u64 v[244:245], v[194:195], 0, v[136:137]
	global_load_lds_dwordx4 v[238:239], off
	v_lshl_add_u64 v[238:239], v[194:195], 0, v[140:141]
	s_mov_b32 m0, s23
	s_nop 0
	global_load_lds_dwordx4 v[238:239], off
	s_mov_b32 m0, s24
	s_nop 0
	global_load_lds_dwordx4 v[244:245], off
	s_cmp_lg_u32 s98, 0
	s_cbranch_scc1 .Lgr_g1_2
	s_waitcnt vmcnt(8)
.Lgr_g1_2:
	s_waitcnt vmcnt(24)
	s_mov_b32 s98, 0
	s_waitcnt lgkmcnt(0)
	s_barrier
	s_waitcnt lgkmcnt(0)
	v_mfma_f32_16x16x32_bf16 v[62:65], v[166:169], v[204:207], v[62:65]
	v_mfma_f32_16x16x32_bf16 v[58:61], v[174:177], v[204:207], v[58:61]
	v_mfma_f32_16x16x32_bf16 v[46:49], v[166:169], v[212:215], v[46:49]
	v_mfma_f32_16x16x32_bf16 v[42:45], v[174:177], v[212:215], v[42:45]
	v_mfma_f32_16x16x32_bf16 v[30:33], v[166:169], v[220:223], v[30:33]
	v_mfma_f32_16x16x32_bf16 v[26:29], v[174:177], v[220:223], v[26:29]
	v_mfma_f32_16x16x32_bf16 v[14:17], v[166:169], v[228:231], v[14:17]
	v_mfma_f32_16x16x32_bf16 v[10:13], v[174:177], v[228:231], v[10:13]
	v_mfma_f32_16x16x32_bf16 v[62:65], v[170:173], v[208:211], v[62:65]
	v_mfma_f32_16x16x32_bf16 v[58:61], v[178:181], v[208:211], v[58:61]
	v_mfma_f32_16x16x32_bf16 v[46:49], v[170:173], v[216:219], v[46:49]
	v_mfma_f32_16x16x32_bf16 v[42:45], v[178:181], v[216:219], v[42:45]
	v_mfma_f32_16x16x32_bf16 v[30:33], v[170:173], v[224:227], v[30:33]
	v_mfma_f32_16x16x32_bf16 v[26:29], v[178:181], v[224:227], v[26:29]
	v_mfma_f32_16x16x32_bf16 v[14:17], v[170:173], v[232:235], v[14:17]
	v_mfma_f32_16x16x32_bf16 v[10:13], v[178:181], v[232:235], v[10:13]
	v_mfma_f32_16x16x32_bf16 v[54:57], v[182:185], v[204:207], v[54:57]
	v_mfma_f32_16x16x32_bf16 v[50:53], v[190:193], v[204:207], v[50:53]
	v_mfma_f32_16x16x32_bf16 v[38:41], v[182:185], v[212:215], v[38:41]
	v_mfma_f32_16x16x32_bf16 v[34:37], v[190:193], v[212:215], v[34:37]
	v_mfma_f32_16x16x32_bf16 v[22:25], v[182:185], v[220:223], v[22:25]
	v_mfma_f32_16x16x32_bf16 v[18:21], v[190:193], v[220:223], v[18:21]
	v_mfma_f32_16x16x32_bf16 v[6:9], v[182:185], v[228:231], v[6:9]
	v_mfma_f32_16x16x32_bf16 v[2:5], v[190:193], v[228:231], v[2:5]
	v_mfma_f32_16x16x32_bf16 v[54:57], v[186:189], v[208:211], v[54:57]
	v_mfma_f32_16x16x32_bf16 v[50:53], v[200:203], v[208:211], v[50:53]
	v_mfma_f32_16x16x32_bf16 v[38:41], v[186:189], v[216:219], v[38:41]
	v_mfma_f32_16x16x32_bf16 v[34:37], v[200:203], v[216:219], v[34:37]
	v_mfma_f32_16x16x32_bf16 v[22:25], v[186:189], v[224:227], v[22:25]
	v_mfma_f32_16x16x32_bf16 v[18:21], v[200:203], v[224:227], v[18:21]
	v_mfma_f32_16x16x32_bf16 v[6:9], v[186:189], v[232:235], v[6:9]
	v_mfma_f32_16x16x32_bf16 v[2:5], v[200:203], v[232:235], v[2:5]
	s_barrier
	s_add_i32 s5, 0, 0x18000
	v_add_u32_e32 v156, s5, v163
	s_add_i32 s8, 0, 0x1c000
	ds_read_b128 v[166:169], v156
	ds_read_b128 v[170:173], v156 offset:1024
	ds_read_b128 v[174:177], v156 offset:2048
	ds_read_b128 v[178:181], v156 offset:3072
	v_add_u32_e32 v156, s8, v163
	ds_read_b128 v[182:185], v156
	ds_read_b128 v[186:189], v156 offset:1024
	ds_read_b128 v[190:193], v156 offset:2048
	ds_read_b128 v[200:203], v156 offset:3072
	v_lshl_add_u64 v[194:195], v[194:195], 0, s[64:65]
	s_mov_b32 m0, s25
	v_lshl_add_u64 v[240:241], v[194:195], 0, v[140:141]
	ds_read_b128 v[204:207], v165 offset:32768
	ds_read_b128 v[208:211], v165 offset:33792
	ds_read_b128 v[212:215], v165 offset:34816
	ds_read_b128 v[216:219], v165 offset:35840
	ds_read_b128 v[220:223], v165 offset:36864
	ds_read_b128 v[224:227], v165 offset:37888
	ds_read_b128 v[228:231], v165 offset:38912
	ds_read_b128 v[232:235], v165 offset:39936
	global_load_lds_dwordx4 v[240:241], off
	v_lshl_add_u64 v[194:195], v[194:195], 0, v[136:137]
	s_mov_b32 m0, s26
	s_nop 0
	global_load_lds_dwordx4 v[194:195], off
	s_waitcnt vmcnt(8)
	s_waitcnt lgkmcnt(0)
	s_barrier
	s_waitcnt lgkmcnt(0)
	v_mfma_f32_16x16x32_bf16 v[126:129], v[166:169], v[204:207], v[126:129]
	v_mfma_f32_16x16x32_bf16 v[122:125], v[174:177], v[204:207], v[122:125]
	v_mfma_f32_16x16x32_bf16 v[110:113], v[166:169], v[212:215], v[110:113]
	v_mfma_f32_16x16x32_bf16 v[106:109], v[174:177], v[212:215], v[106:109]
	v_mfma_f32_16x16x32_bf16 v[94:97], v[166:169], v[220:223], v[94:97]
	v_mfma_f32_16x16x32_bf16 v[90:93], v[174:177], v[220:223], v[90:93]
	v_mfma_f32_16x16x32_bf16 v[78:81], v[166:169], v[228:231], v[78:81]
	v_mfma_f32_16x16x32_bf16 v[74:77], v[174:177], v[228:231], v[74:77]
	v_mfma_f32_16x16x32_bf16 v[126:129], v[170:173], v[208:211], v[126:129]
	v_mfma_f32_16x16x32_bf16 v[122:125], v[178:181], v[208:211], v[122:125]
	v_mfma_f32_16x16x32_bf16 v[110:113], v[170:173], v[216:219], v[110:113]
	v_mfma_f32_16x16x32_bf16 v[106:109], v[178:181], v[216:219], v[106:109]
	v_mfma_f32_16x16x32_bf16 v[94:97], v[170:173], v[224:227], v[94:97]
	v_mfma_f32_16x16x32_bf16 v[90:93], v[178:181], v[224:227], v[90:93]
	v_mfma_f32_16x16x32_bf16 v[78:81], v[170:173], v[232:235], v[78:81]
	v_mfma_f32_16x16x32_bf16 v[74:77], v[178:181], v[232:235], v[74:77]
	v_mfma_f32_16x16x32_bf16 v[118:121], v[182:185], v[204:207], v[118:121]
	v_mfma_f32_16x16x32_bf16 v[114:117], v[190:193], v[204:207], v[114:117]
	v_mfma_f32_16x16x32_bf16 v[102:105], v[182:185], v[212:215], v[102:105]
	v_mfma_f32_16x16x32_bf16 v[98:101], v[190:193], v[212:215], v[98:101]
	v_mfma_f32_16x16x32_bf16 v[86:89], v[182:185], v[220:223], v[86:89]
	v_mfma_f32_16x16x32_bf16 v[82:85], v[190:193], v[220:223], v[82:85]
	v_mfma_f32_16x16x32_bf16 v[70:73], v[182:185], v[228:231], v[70:73]
	v_mfma_f32_16x16x32_bf16 v[66:69], v[190:193], v[228:231], v[66:69]
	v_mfma_f32_16x16x32_bf16 v[118:121], v[186:189], v[208:211], v[118:121]
	v_mfma_f32_16x16x32_bf16 v[114:117], v[200:203], v[208:211], v[114:117]
	v_mfma_f32_16x16x32_bf16 v[102:105], v[186:189], v[216:219], v[102:105]
	v_mfma_f32_16x16x32_bf16 v[98:101], v[200:203], v[216:219], v[98:101]
	v_mfma_f32_16x16x32_bf16 v[86:89], v[186:189], v[224:227], v[86:89]
	v_mfma_f32_16x16x32_bf16 v[82:85], v[200:203], v[224:227], v[82:85]
	v_mfma_f32_16x16x32_bf16 v[70:73], v[186:189], v[232:235], v[70:73]
	v_mfma_f32_16x16x32_bf16 v[66:69], v[200:203], v[232:235], v[66:69]
	s_barrier
	s_add_i32 s5, s5, s22
	v_lshl_add_u64 v[194:195], v[252:253], 0, s[62:63]
	s_mov_b32 m0, s5
	ds_read_b128 v[204:207], v165 offset:49152
	ds_read_b128 v[208:211], v165 offset:50176
	ds_read_b128 v[212:215], v165 offset:51200
	ds_read_b128 v[216:219], v165 offset:52224
	ds_read_b128 v[220:223], v165 offset:53248
	ds_read_b128 v[224:227], v165 offset:54272
	ds_read_b128 v[228:231], v165 offset:55296
	ds_read_b128 v[232:235], v165 offset:56320
	global_load_lds_dwordx4 v[194:195], off
	v_lshl_add_u64 v[194:195], v[242:243], 0, s[62:63]
	s_add_i32 m0, s5, 0x2000
	s_add_i32 s5, s8, s22
	global_load_lds_dwordx4 v[194:195], off
	v_lshl_add_u64 v[194:195], v[236:237], 0, s[84:85]
	v_lshl_add_u64 v[236:237], v[194:195], 0, v[138:139]
	s_mov_b32 m0, s5
	v_lshl_add_u64 v[194:195], v[194:195], 0, v[134:135]
	global_load_lds_dwordx4 v[236:237], off
	s_add_i32 m0, s5, 0x2000
	s_nop 0
	global_load_lds_dwordx4 v[194:195], off
	v_lshl_add_u64 v[194:195], v[238:239], 0, s[62:63]
	s_mov_b32 m0, s27
	s_nop 0
	global_load_lds_dwordx4 v[194:195], off
	v_lshl_add_u64 v[194:195], v[244:245], 0, s[62:63]
	s_mov_b32 m0, s28
	s_nop 0
	global_load_lds_dwordx4 v[194:195], off
	s_waitcnt vmcnt(8)
	s_waitcnt lgkmcnt(0)
	s_barrier
	s_waitcnt lgkmcnt(0)
	v_mfma_f32_16x16x32_bf16 v[62:65], v[166:169], v[204:207], v[62:65]
	v_mfma_f32_16x16x32_bf16 v[58:61], v[174:177], v[204:207], v[58:61]
	v_mfma_f32_16x16x32_bf16 v[46:49], v[166:169], v[212:215], v[46:49]
	v_mfma_f32_16x16x32_bf16 v[42:45], v[174:177], v[212:215], v[42:45]
	v_mfma_f32_16x16x32_bf16 v[30:33], v[166:169], v[220:223], v[30:33]
	v_mfma_f32_16x16x32_bf16 v[26:29], v[174:177], v[220:223], v[26:29]
	v_mfma_f32_16x16x32_bf16 v[14:17], v[166:169], v[228:231], v[14:17]
	v_mfma_f32_16x16x32_bf16 v[10:13], v[174:177], v[228:231], v[10:13]
	v_mfma_f32_16x16x32_bf16 v[62:65], v[170:173], v[208:211], v[62:65]
	v_mfma_f32_16x16x32_bf16 v[58:61], v[178:181], v[208:211], v[58:61]
	v_mfma_f32_16x16x32_bf16 v[46:49], v[170:173], v[216:219], v[46:49]
	v_mfma_f32_16x16x32_bf16 v[42:45], v[178:181], v[216:219], v[42:45]
	v_mfma_f32_16x16x32_bf16 v[30:33], v[170:173], v[224:227], v[30:33]
	v_mfma_f32_16x16x32_bf16 v[26:29], v[178:181], v[224:227], v[26:29]
	v_mfma_f32_16x16x32_bf16 v[14:17], v[170:173], v[232:235], v[14:17]
	v_mfma_f32_16x16x32_bf16 v[10:13], v[178:181], v[232:235], v[10:13]
	v_mfma_f32_16x16x32_bf16 v[54:57], v[182:185], v[204:207], v[54:57]
	v_mfma_f32_16x16x32_bf16 v[50:53], v[190:193], v[204:207], v[50:53]
	v_mfma_f32_16x16x32_bf16 v[38:41], v[182:185], v[212:215], v[38:41]
	v_mfma_f32_16x16x32_bf16 v[34:37], v[190:193], v[212:215], v[34:37]
	v_mfma_f32_16x16x32_bf16 v[22:25], v[182:185], v[220:223], v[22:25]
	v_mfma_f32_16x16x32_bf16 v[18:21], v[190:193], v[220:223], v[18:21]
	v_mfma_f32_16x16x32_bf16 v[6:9], v[182:185], v[228:231], v[6:9]
	v_mfma_f32_16x16x32_bf16 v[2:5], v[190:193], v[228:231], v[2:5]
	v_mfma_f32_16x16x32_bf16 v[54:57], v[186:189], v[208:211], v[54:57]
	v_mfma_f32_16x16x32_bf16 v[50:53], v[200:203], v[208:211], v[50:53]
	v_mfma_f32_16x16x32_bf16 v[38:41], v[186:189], v[216:219], v[38:41]
	v_mfma_f32_16x16x32_bf16 v[34:37], v[200:203], v[216:219], v[34:37]
	v_mfma_f32_16x16x32_bf16 v[22:25], v[186:189], v[224:227], v[22:25]
	v_mfma_f32_16x16x32_bf16 v[18:21], v[200:203], v[224:227], v[18:21]
	v_mfma_f32_16x16x32_bf16 v[6:9], v[186:189], v[232:235], v[6:9]
	v_mfma_f32_16x16x32_bf16 v[2:5], v[200:203], v[232:235], v[2:5]
	s_barrier
	s_add_i32 s4, s4, 2
	v_lshl_add_u64 v[158:159], v[158:159], 0, s[86:87]
	s_cmp_gt_u32 s4, 13
	v_lshl_add_u64 v[160:161], v[160:161], 0, s[86:87]
	s_cbranch_scc0 .LBB0_150
	s_and_b64 vcc, exec, s[14:15]
	s_cbranch_vccz .LBB0_153
	s_barrier
